# M9 + de-serialised loads: hyfin X0 rows, conv Z staging, P7 cvtq_tile W rows (all loads of a tile issued up front)
# speedup vs baseline: 1.0067x; 1.0067x over previous
.LBB0_705:
	s_ashr_i32 s18, s4, 1
	s_nop 1
	v_mov_b32_e32 v6, v0
	s_mul_i32 s6, s18, 0x18000
	s_mul_hi_i32 s7, s18, 0x18000
	s_add_u32 s6, s16, s6
	v_lshlrev_b32_e32 v4, 4, v6
	s_addc_u32 s7, s17, s7
	v_and_b32_e32 v2, 0xff0, v4
	v_ashrrev_i32_e32 v7, 31, v6
	v_add_u32_e32 v5, 0, v2
	s_waitcnt lgkmcnt(0)
	v_lshl_add_u64 v[2:3], v[6:7], 4, s[6:7]
	global_load_dwordx4 v[12:15], v[2:3], off
	v_add_co_u32_e32 v8, vcc, 0x2000, v2
	s_nop 1
	v_addc_co_u32_e32 v9, vcc, 0, v3, vcc
	global_load_dwordx4 v[16:19], v[8:9], off
	v_add_co_u32_e32 v8, vcc, 0x4000, v2
	s_nop 1
	v_addc_co_u32_e32 v9, vcc, 0, v3, vcc
	global_load_dwordx4 v[20:23], v[8:9], off
	v_add_co_u32_e32 v8, vcc, 0x6000, v2
	s_nop 1
	v_addc_co_u32_e32 v9, vcc, 0, v3, vcc
	global_load_dwordx4 v[24:27], v[8:9], off
	v_add_co_u32_e32 v8, vcc, 0x8000, v2
	s_nop 1
	v_addc_co_u32_e32 v9, vcc, 0, v3, vcc
	global_load_dwordx4 v[28:31], v[8:9], off
	v_add_co_u32_e32 v8, vcc, 0xa000, v2
	s_nop 1
	v_addc_co_u32_e32 v9, vcc, 0, v3, vcc
	global_load_dwordx4 v[32:35], v[8:9], off
	v_add_co_u32_e32 v8, vcc, 0xc000, v2
	s_nop 1
	v_addc_co_u32_e32 v9, vcc, 0, v3, vcc
	global_load_dwordx4 v[36:39], v[8:9], off
	v_add_co_u32_e32 v8, vcc, 0xe000, v2
	s_nop 1
	v_addc_co_u32_e32 v9, vcc, 0, v3, vcc
	global_load_dwordx4 v[40:43], v[8:9], off
	v_add_co_u32_e32 v8, vcc, 0x10000, v2
	s_nop 1
	v_addc_co_u32_e32 v9, vcc, 0, v3, vcc
	global_load_dwordx4 v[44:47], v[8:9], off
	v_add_co_u32_e32 v8, vcc, 0x12000, v2
	s_nop 1
	v_addc_co_u32_e32 v9, vcc, 0, v3, vcc
	global_load_dwordx4 v[48:51], v[8:9], off
	v_add_co_u32_e32 v8, vcc, 0x14000, v2
	s_nop 1
	v_addc_co_u32_e32 v9, vcc, 0, v3, vcc
	global_load_dwordx4 v[52:55], v[8:9], off
	v_add_co_u32_e32 v8, vcc, 0x16000, v2
	s_nop 1
	v_addc_co_u32_e32 v9, vcc, 0, v3, vcc
	global_load_dwordx4 v[56:59], v[8:9], off
	v_lshrrev_b32_e32 v7, 8, v6
	s_movk_i32 s7, 0x1010
	v_mad_i32_i24 v7, v7, s7, v5
	s_mov_b32 s6, 0xa000
	s_waitcnt vmcnt(11)
	ds_write_b128 v7, v[12:15]
	v_add_u32_e32 v7, 0x200, v6
	s_nop 0
	v_lshrrev_b32_e32 v7, 8, v7
	v_mad_i32_i24 v7, v7, s7, v5
	s_waitcnt vmcnt(10)
	ds_write_b128 v7, v[16:19]
	v_add_u32_e32 v7, 0x400, v6
	s_nop 0
	v_lshrrev_b32_e32 v7, 8, v7
	v_mad_i32_i24 v7, v7, s7, v5
	s_waitcnt vmcnt(9)
	ds_write_b128 v7, v[20:23]
	v_add_u32_e32 v7, 0x600, v6
	s_nop 0
	v_lshrrev_b32_e32 v7, 8, v7
	v_mad_i32_i24 v7, v7, s7, v5
	s_waitcnt vmcnt(8)
	ds_write_b128 v7, v[24:27]
	v_add_u32_e32 v7, 0x800, v6
	s_nop 0
	v_lshrrev_b32_e32 v7, 8, v7
	v_mad_i32_i24 v7, v7, s7, v5
	s_waitcnt vmcnt(7)
	ds_write_b128 v7, v[28:31]
	v_add_u32_e32 v7, 0xa00, v6
	s_nop 0
	v_lshrrev_b32_e32 v7, 8, v7
	v_mad_i32_i24 v7, v7, s7, v5
	s_mov_b32 s6, 0xc000
	s_waitcnt vmcnt(6)
	ds_write_b128 v7, v[32:35]
	v_add_u32_e32 v7, 0xc00, v6
	s_nop 0
	v_lshrrev_b32_e32 v7, 8, v7
	v_mad_i32_i24 v7, v7, s7, v5
	s_mov_b32 s6, 0xe000
	s_waitcnt vmcnt(5)
	ds_write_b128 v7, v[36:39]
	v_add_u32_e32 v7, 0xe00, v6
	s_nop 0
	v_lshrrev_b32_e32 v7, 8, v7
	v_mad_i32_i24 v7, v7, s7, v5
	s_mov_b32 s6, 0x10000
	s_waitcnt vmcnt(4)
	ds_write_b128 v7, v[40:43]
	v_add_u32_e32 v7, 0x1000, v6
	s_nop 0
	v_lshrrev_b32_e32 v7, 8, v7
	v_mad_i32_i24 v7, v7, s7, v5
	s_mov_b32 s6, 0x12000
	s_waitcnt vmcnt(3)
	ds_write_b128 v7, v[44:47]
	v_add_u32_e32 v7, 0x1200, v6
	s_nop 0
	v_lshrrev_b32_e32 v7, 8, v7
	v_mad_i32_i24 v7, v7, s7, v5
	s_mov_b32 s6, 0x14000
	s_waitcnt vmcnt(2)
	ds_write_b128 v7, v[48:51]
	v_add_u32_e32 v7, 0x1400, v6
	s_nop 0
	v_lshrrev_b32_e32 v7, 8, v7
	v_mad_i32_i24 v7, v7, s7, v5
	s_nop 0
	s_movk_i32 s6, 0x202
	v_cmp_gt_i32_e32 vcc, s6, v6
	s_waitcnt vmcnt(1)
	ds_write_b128 v7, v[52:55]
	v_add_u32_e32 v7, 0x1600, v6
	v_lshrrev_b32_e32 v2, 8, v7
	v_mad_i32_i24 v2, v2, s7, v5
	s_waitcnt vmcnt(0)
	ds_write_b128 v2, v[56:59]
	s_and_saveexec_b64 s[6:7], vcc
	s_cbranch_execz .LBB0_722
	s_mul_i32 s8, s18, 0x2020
	s_mul_hi_i32 s9, s18, 0x2020
	s_add_u32 s8, s14, s8
	v_readlane_b32 s10, v254, 57
	s_addc_u32 s9, s15, s9
	v_lshlrev_b32_e32 v8, 3, v6
	v_add_u32_e32 v7, s10, v4
	s_mov_b64 s[10:11], 0
	v_mov_b32_e32 v10, v6
	s_branch .LBB0_708

.LBB0_809:
	s_ashr_i32 s6, s25, 6
	s_and_b32 s7, s8, 0x7e0
	v_add_u32_e32 v28, s7, v58
	s_ashr_i32 s7, s6, 31
	v_ashrrev_i32_e32 v29, 31, v28
	v_lshl_add_u64 v[2:3], s[6:7], 0, v[114:115]
	v_lshl_add_u64 v[6:7], s[6:7], 0, v[18:19]
	v_lshl_add_u64 v[10:11], s[6:7], 0, v[20:21]
	v_lshl_add_u64 v[16:17], s[6:7], 0, v[22:23]
	s_lshl_b64 s[6:7], s[6:7], 11
	v_lshl_add_u64 v[14:15], v[28:29], 1, s[0:1]
	v_lshl_add_u64 v[28:29], s[6:7], 0, v[28:29]
	v_lshlrev_b64 v[2:3], 12, v[2:3]
	v_lshlrev_b64 v[6:7], 12, v[6:7]
	v_lshlrev_b64 v[10:11], 12, v[10:11]
	v_lshlrev_b64 v[16:17], 12, v[16:17]
	v_lshlrev_b64 v[30:31], 10, v[28:29]
	v_lshl_add_u64 v[2:3], v[14:15], 0, v[2:3]
	v_lshl_add_u64 v[6:7], v[14:15], 0, v[6:7]
	v_lshl_add_u64 v[10:11], v[14:15], 0, v[10:11]
	v_lshl_add_u64 v[14:15], v[14:15], 0, v[16:17]
	v_lshl_add_u64 v[44:45], v[24:25], 0, v[30:31]
	global_load_dwordx4 v[2:5], v[2:3], off
	s_nop 0
	global_load_dwordx4 v[6:9], v[6:7], off
	s_waitcnt vmcnt(1)
	v_lshlrev_b32_e32 v32, 16, v2
	global_load_dwordx4 v[10:13], v[10:11], off
	s_waitcnt vmcnt(1)
	v_lshlrev_b32_e32 v36, 16, v6
	global_load_dwordx4 v[14:17], v[14:15], off
	v_and_b32_e32 v40, 0xffff0000, v6
	global_load_dwordx2 v[70:71], v[44:45], off
	global_load_dwordx2 v[72:73], v[44:45], off offset:1024
	global_load_dwordx2 v[74:75], v[44:45], off offset:2048
	global_load_dwordx2 v[76:77], v[44:45], off offset:3072
	v_add_co_u32_e32 v68, vcc, s63, v44
	s_nop 1
	v_addc_co_u32_e32 v69, vcc, 0, v45, vcc
	global_load_dwordx2 v[78:79], v[68:69], off
	global_load_dwordx2 v[80:81], v[68:69], off offset:1024
	global_load_dwordx2 v[82:83], v[68:69], off offset:2048
	global_load_dwordx2 v[84:85], v[68:69], off offset:3072
	v_lshlrev_b32_e32 v42, 16, v7
	s_waitcnt vmcnt(9)
	v_lshlrev_b32_e32 v33, 16, v10
	s_waitcnt vmcnt(8)
	v_lshlrev_b32_e32 v37, 16, v14
	v_and_b32_e32 v41, 0xffff0000, v14
	s_waitcnt vmcnt(7)
	v_lshlrev_b32_e32 v35, 16, v71
	v_lshlrev_b32_e32 v34, 16, v70
	v_and_b32_e32 v31, 0xffff0000, v71
	v_and_b32_e32 v30, 0xffff0000, v70
	v_pk_mul_f32 v[36:37], v[36:37], v[30:31]
	v_pk_mul_f32 v[34:35], v[32:33], v[34:35]
	v_and_b32_e32 v33, 0xffff0000, v10
	v_and_b32_e32 v32, 0xffff0000, v2
	v_lshlrev_b32_e32 v43, 16, v15
	v_and_b32_e32 v10, 0xffff0000, v3
	v_and_b32_e32 v2, 0xffff0000, v7
	s_waitcnt vmcnt(6)
	v_lshlrev_b32_e32 v39, 16, v73
	v_lshlrev_b32_e32 v38, 16, v72
	v_and_b32_e32 v31, 0xffff0000, v73
	v_and_b32_e32 v30, 0xffff0000, v72
	v_pk_mul_f32 v[40:41], v[40:41], v[30:31]
	v_pk_mul_f32 v[38:39], v[32:33], v[38:39]
	v_lshlrev_b32_e32 v33, 16, v11
	v_lshlrev_b32_e32 v32, 16, v3
	v_and_b32_e32 v3, 0xffff0000, v15
	v_and_b32_e32 v11, 0xffff0000, v11
	s_waitcnt vmcnt(5)
	v_lshlrev_b32_e32 v47, 16, v75
	v_lshlrev_b32_e32 v46, 16, v74
	v_and_b32_e32 v49, 0xffff0000, v75
	v_and_b32_e32 v48, 0xffff0000, v74
	v_pk_mul_f32 v[30:31], v[32:33], v[46:47]
	v_pk_mul_f32 v[32:33], v[42:43], v[48:49]
	v_lshlrev_b32_e32 v47, 16, v16
	v_lshlrev_b32_e32 v46, 16, v8
	v_and_b32_e32 v49, 0xffff0000, v16
	v_and_b32_e32 v48, 0xffff0000, v8
	s_waitcnt vmcnt(4)
	v_lshlrev_b32_e32 v7, 16, v77
	v_lshlrev_b32_e32 v6, 16, v76
	v_and_b32_e32 v43, 0xffff0000, v77
	v_and_b32_e32 v42, 0xffff0000, v76
	v_pk_mul_f32 v[42:43], v[2:3], v[42:43]
	v_pk_mul_f32 v[14:15], v[10:11], v[6:7]
	s_nop 0
	v_lshlrev_b32_e32 v11, 16, v12
	v_lshlrev_b32_e32 v10, 16, v4
	s_waitcnt vmcnt(3)
	v_lshlrev_b32_e32 v45, 16, v79
	v_lshlrev_b32_e32 v44, 16, v78
	v_and_b32_e32 v7, 0xffff0000, v79
	v_and_b32_e32 v6, 0xffff0000, v78
	v_pk_mul_f32 v[46:47], v[46:47], v[6:7]
	v_pk_mul_f32 v[44:45], v[10:11], v[44:45]
	v_and_b32_e32 v11, 0xffff0000, v12
	v_and_b32_e32 v10, 0xffff0000, v4
	v_and_b32_e32 v4, 0xffff0000, v9
	s_waitcnt vmcnt(2)
	v_lshlrev_b32_e32 v51, 16, v81
	v_lshlrev_b32_e32 v50, 16, v80
	v_and_b32_e32 v7, 0xffff0000, v81
	v_and_b32_e32 v6, 0xffff0000, v80
	v_pk_mul_f32 v[54:55], v[48:49], v[6:7]
	v_pk_mul_f32 v[52:53], v[10:11], v[50:51]
	v_lshlrev_b32_e32 v51, 16, v17
	v_lshlrev_b32_e32 v50, 16, v9
	v_lshlrev_b32_e32 v10, 16, v5
	v_lshlrev_b32_e32 v11, 16, v13
	s_waitcnt vmcnt(1)
	v_lshlrev_b32_e32 v49, 16, v83
	v_lshlrev_b32_e32 v48, 16, v82
	v_and_b32_e32 v7, 0xffff0000, v83
	v_and_b32_e32 v6, 0xffff0000, v82
	v_pk_mul_f32 v[50:51], v[50:51], v[6:7]
	v_and_b32_e32 v6, 0xffff0000, v5
	v_and_b32_e32 v5, 0xffff0000, v17
	s_waitcnt vmcnt(0)
	v_lshlrev_b32_e32 v9, 16, v85
	v_lshlrev_b32_e32 v8, 16, v84
	v_and_b32_e32 v3, 0xffff0000, v85
	v_and_b32_e32 v2, 0xffff0000, v84
	v_and_b32_e32 v7, 0xffff0000, v13
	v_pk_mul_f32 v[56:57], v[4:5], v[2:3]
	v_mov_b32_e32 v4, v36
	v_mov_b32_e32 v5, v40
	v_pk_mul_f32 v[16:17], v[6:7], v[8:9]
	v_mov_b32_e32 v2, v34
	v_mov_b32_e32 v3, v38
	v_pk_mul_f32 v[4:5], v[4:5], v[4:5]
	v_mov_b32_e32 v6, v37
	v_mov_b32_e32 v7, v41
	v_pk_fma_f32 v[2:3], v[2:3], v[2:3], v[4:5]
	v_mov_b32_e32 v4, v35
	v_mov_b32_e32 v5, v39
	v_pk_mul_f32 v[6:7], v[6:7], v[6:7]
	v_mov_b32_e32 v8, v33
	v_pk_fma_f32 v[4:5], v[4:5], v[4:5], v[6:7]
	v_mov_b32_e32 v9, v43
	v_pk_add_f32 v[2:3], v[2:3], v[4:5]
	ds_bpermute_b32 v4, v184, v2
	ds_bpermute_b32 v5, v184, v3
	v_pk_mul_f32 v[8:9], v[8:9], v[8:9]
	v_pk_mul_f32 v[48:49], v[10:11], v[48:49]
	v_mov_b32_e32 v10, v47
	v_mov_b32_e32 v11, v55
	s_waitcnt lgkmcnt(0)
	v_pk_add_f32 v[2:3], v[2:3], v[4:5]
	ds_bpermute_b32 v4, v185, v2
	ds_bpermute_b32 v5, v185, v3
	v_pk_mul_f32 v[10:11], v[10:11], v[10:11]
	v_mov_b32_e32 v12, v51
	v_mov_b32_e32 v13, v57
	v_pk_mul_f32 v[12:13], v[12:13], v[12:13]
	s_waitcnt lgkmcnt(0)
	v_pk_add_f32 v[2:3], v[2:3], v[4:5]
	ds_bpermute_b32 v4, v186, v2
	ds_bpermute_b32 v5, v186, v3
	s_waitcnt lgkmcnt(0)
	v_pk_add_f32 v[2:3], v[2:3], v[4:5]
	ds_bpermute_b32 v4, v187, v2
	ds_bpermute_b32 v5, v187, v3
	s_waitcnt lgkmcnt(0)
	v_pk_add_f32 v[2:3], v[2:3], v[4:5]
	ds_bpermute_b32 v4, v188, v2
	ds_bpermute_b32 v5, v188, v3
	s_waitcnt lgkmcnt(0)
	v_pk_add_f32 v[2:3], v[2:3], v[4:5]
	ds_bpermute_b32 v4, v189, v2
	ds_bpermute_b32 v5, v189, v3
	s_waitcnt lgkmcnt(0)
	v_pk_add_f32 v[6:7], v[2:3], v[4:5]
	v_mov_b32_e32 v4, v32
	v_mov_b32_e32 v5, v42
	v_mov_b32_e32 v2, v30
	v_mov_b32_e32 v3, v14
	v_pk_mul_f32 v[4:5], v[4:5], v[4:5]
	s_nop 0
	v_pk_fma_f32 v[2:3], v[2:3], v[2:3], v[4:5]
	v_mov_b32_e32 v4, v31
	v_mov_b32_e32 v5, v15
	v_pk_fma_f32 v[4:5], v[4:5], v[4:5], v[8:9]
	s_nop 0
	v_pk_add_f32 v[2:3], v[2:3], v[4:5]
	ds_bpermute_b32 v4, v184, v2
	ds_bpermute_b32 v5, v184, v3
	s_waitcnt lgkmcnt(0)
	v_pk_add_f32 v[2:3], v[2:3], v[4:5]
	ds_bpermute_b32 v4, v185, v2
	ds_bpermute_b32 v5, v185, v3
	s_waitcnt lgkmcnt(0)
	v_pk_add_f32 v[2:3], v[2:3], v[4:5]
	ds_bpermute_b32 v4, v186, v2
	ds_bpermute_b32 v5, v186, v3
	s_waitcnt lgkmcnt(0)
	v_pk_add_f32 v[2:3], v[2:3], v[4:5]
	ds_bpermute_b32 v4, v187, v2
	ds_bpermute_b32 v5, v187, v3
	s_waitcnt lgkmcnt(0)
	v_pk_add_f32 v[2:3], v[2:3], v[4:5]
	ds_bpermute_b32 v4, v188, v2
	ds_bpermute_b32 v5, v188, v3
	s_waitcnt lgkmcnt(0)
	v_pk_add_f32 v[2:3], v[2:3], v[4:5]
	ds_bpermute_b32 v4, v189, v2
	ds_bpermute_b32 v5, v189, v3
	s_waitcnt lgkmcnt(0)
	v_pk_add_f32 v[8:9], v[2:3], v[4:5]
	v_mov_b32_e32 v4, v46
	v_mov_b32_e32 v5, v54
	v_mov_b32_e32 v2, v44
	v_mov_b32_e32 v3, v52
	v_pk_mul_f32 v[4:5], v[4:5], v[4:5]
	s_nop 0
	v_pk_fma_f32 v[2:3], v[2:3], v[2:3], v[4:5]
	v_mov_b32_e32 v4, v45
	v_mov_b32_e32 v5, v53
	v_pk_fma_f32 v[4:5], v[4:5], v[4:5], v[10:11]
	v_mov_b32_e32 v10, v50
	v_pk_add_f32 v[2:3], v[2:3], v[4:5]
	ds_bpermute_b32 v4, v184, v2
	ds_bpermute_b32 v5, v184, v3
	v_mov_b32_e32 v11, v56
	v_pk_mul_f32 v[10:11], v[10:11], v[10:11]
	s_waitcnt lgkmcnt(0)
	v_pk_add_f32 v[2:3], v[2:3], v[4:5]
	ds_bpermute_b32 v4, v185, v2
	ds_bpermute_b32 v5, v185, v3
	s_waitcnt lgkmcnt(0)
	v_pk_add_f32 v[2:3], v[2:3], v[4:5]
	ds_bpermute_b32 v4, v186, v2
	ds_bpermute_b32 v5, v186, v3
	s_waitcnt lgkmcnt(0)
	v_pk_add_f32 v[2:3], v[2:3], v[4:5]
	ds_bpermute_b32 v4, v187, v2
	ds_bpermute_b32 v5, v187, v3
	s_waitcnt lgkmcnt(0)
	v_pk_add_f32 v[2:3], v[2:3], v[4:5]
	ds_bpermute_b32 v4, v188, v2
	ds_bpermute_b32 v5, v188, v3
	s_waitcnt lgkmcnt(0)
	v_pk_add_f32 v[2:3], v[2:3], v[4:5]
	ds_bpermute_b32 v4, v189, v2
	ds_bpermute_b32 v5, v189, v3
	s_waitcnt lgkmcnt(0)
	v_pk_add_f32 v[2:3], v[2:3], v[4:5]
	v_mov_b32_e32 v4, v48
	v_mov_b32_e32 v5, v16
	v_pk_fma_f32 v[4:5], v[4:5], v[4:5], v[10:11]
	v_mov_b32_e32 v10, v49
	v_mov_b32_e32 v11, v17
	v_pk_fma_f32 v[10:11], v[10:11], v[10:11], v[12:13]
	s_nop 0
	v_pk_add_f32 v[4:5], v[4:5], v[10:11]
	ds_bpermute_b32 v10, v184, v4
	ds_bpermute_b32 v11, v184, v5
	s_waitcnt lgkmcnt(0)
	v_pk_add_f32 v[4:5], v[4:5], v[10:11]
	ds_bpermute_b32 v10, v185, v4
	ds_bpermute_b32 v11, v185, v5
	s_waitcnt lgkmcnt(0)
	v_pk_add_f32 v[4:5], v[4:5], v[10:11]
	ds_bpermute_b32 v10, v186, v4
	ds_bpermute_b32 v11, v186, v5
	s_waitcnt lgkmcnt(0)
	v_pk_add_f32 v[4:5], v[4:5], v[10:11]
	ds_bpermute_b32 v10, v187, v4
	ds_bpermute_b32 v11, v187, v5
	s_waitcnt lgkmcnt(0)
	v_pk_add_f32 v[4:5], v[4:5], v[10:11]
	ds_bpermute_b32 v10, v188, v4
	ds_bpermute_b32 v11, v188, v5
	s_waitcnt lgkmcnt(0)
	v_pk_add_f32 v[4:5], v[4:5], v[10:11]
	ds_bpermute_b32 v10, v189, v4
	ds_bpermute_b32 v11, v189, v5
	s_waitcnt lgkmcnt(0)
	v_pk_add_f32 v[4:5], v[4:5], v[10:11]
	s_and_saveexec_b64 s[6:7], s[36:37]
	s_cbranch_execz .LBB0_808
	s_add_i32 s10, s3, 0
	v_mov_b32_e32 v10, s10
	ds_write_b128 v10, v[6:9]
	ds_write_b128 v10, v[2:5] offset:16
	s_branch .LBB0_808

.LBB0_1034:
	s_ashr_i32 s13, s25, 4
	s_lshl_b32 s14, s13, 8
	s_lshl_b32 s12, s13, 7
	s_and_b32 s15, s4, 0x780
	s_add_i32 s16, s14, 0xffffd420
	s_cmp_lt_i32 s13, 44
	s_cselect_b32 s14, s14, s16
	s_ashr_i32 s13, s12, 31
	s_lshl_b64 s[12:13], s[12:13], 2
	v_lshl_add_u64 v[2:3], v[6:7], 0, s[12:13]
	global_load_dwordx4 v[2:5], v[2:3], off nt
	v_lshl_add_u64 v[12:13], v[8:9], 0, s[12:13]
	v_add_u32_e32 v120, s15, v43
	v_ashrrev_i32_e32 v121, 31, v120
	v_mad_i64_i32 v[122:123], s[12:13], v120, s18, v[12:13]
	v_lshl_add_u64 v[124:125], v[120:121], 2, s[10:11]
	global_load_dwordx4 v[68:71], v[122:123], off nt
	global_load_dword v100, v[124:125], off
	v_add_u32_e32 v120, s15, v44
	v_ashrrev_i32_e32 v121, 31, v120
	v_mad_i64_i32 v[122:123], s[12:13], v120, s18, v[12:13]
	v_lshl_add_u64 v[124:125], v[120:121], 2, s[10:11]
	global_load_dwordx4 v[72:75], v[122:123], off nt
	global_load_dword v102, v[124:125], off
	v_add_u32_e32 v120, s15, v45
	v_ashrrev_i32_e32 v121, 31, v120
	v_mad_i64_i32 v[122:123], s[12:13], v120, s18, v[12:13]
	v_lshl_add_u64 v[124:125], v[120:121], 2, s[10:11]
	global_load_dwordx4 v[76:79], v[122:123], off nt
	global_load_dword v104, v[124:125], off
	v_add_u32_e32 v120, s15, v46
	v_ashrrev_i32_e32 v121, 31, v120
	v_mad_i64_i32 v[122:123], s[12:13], v120, s18, v[12:13]
	v_lshl_add_u64 v[124:125], v[120:121], 2, s[10:11]
	global_load_dwordx4 v[80:83], v[122:123], off nt
	global_load_dword v106, v[124:125], off
	v_add_u32_e32 v120, s15, v47
	v_ashrrev_i32_e32 v121, 31, v120
	v_mad_i64_i32 v[122:123], s[12:13], v120, s18, v[12:13]
	v_lshl_add_u64 v[124:125], v[120:121], 2, s[10:11]
	global_load_dwordx4 v[84:87], v[122:123], off nt
	global_load_dword v108, v[124:125], off
	v_add_u32_e32 v120, s15, v48
	v_ashrrev_i32_e32 v121, 31, v120
	v_mad_i64_i32 v[122:123], s[12:13], v120, s18, v[12:13]
	v_lshl_add_u64 v[124:125], v[120:121], 2, s[10:11]
	global_load_dwordx4 v[88:91], v[122:123], off nt
	global_load_dword v110, v[124:125], off
	v_add_u32_e32 v120, s15, v49
	v_ashrrev_i32_e32 v121, 31, v120
	v_mad_i64_i32 v[122:123], s[12:13], v120, s18, v[12:13]
	v_lshl_add_u64 v[124:125], v[120:121], 2, s[10:11]
	global_load_dwordx4 v[92:95], v[122:123], off nt
	global_load_dword v112, v[124:125], off
	v_add_u32_e32 v120, s15, v50
	v_ashrrev_i32_e32 v121, 31, v120
	v_mad_i64_i32 v[122:123], s[12:13], v120, s18, v[12:13]
	v_lshl_add_u64 v[124:125], v[120:121], 2, s[10:11]
	global_load_dwordx4 v[96:99], v[122:123], off nt
	global_load_dword v118, v[124:125], off
	s_waitcnt vmcnt(16)
	v_max_f32_e32 v2, v2, v2
	v_max_f32_e32 v2, 0xda24260, v2
	v_div_scale_f32 v3, s[16:17], v2, v2, s47
	v_rcp_f32_e32 v4, v3
	s_nop 0
	v_fma_f32 v5, -v3, v4, 1.0
	v_fmac_f32_e32 v4, v5, v4
	v_div_scale_f32 v5, vcc, s47, v2, s47
	v_mul_f32_e32 v10, v5, v4
	v_fma_f32 v11, -v3, v10, v5
	v_fmac_f32_e32 v10, v11, v4
	v_fma_f32 v3, -v3, v10, v5
	v_div_fmas_f32 v3, v3, v4, v10
	v_div_fixup_f32 v10, v3, v2, s47
	s_nop 0
	s_waitcnt vmcnt(14)
	v_pk_mul_f32 v[2:3], v[68:69], v[100:101] op_sel_hi:[1,0]
	v_pk_mul_f32 v[4:5], v[70:71], v[100:101] op_sel_hi:[1,0]
	v_pk_mul_f32 v[2:3], v[10:11], v[2:3] op_sel_hi:[0,1]
	v_pk_mul_f32 v[4:5], v[10:11], v[4:5] op_sel_hi:[0,1]
	ds_write2_b32 v55, v2, v3 offset1:1
	ds_write2_b32 v55, v4, v5 offset0:2 offset1:3
	s_nop 0
	s_waitcnt vmcnt(12)
	v_pk_mul_f32 v[2:3], v[72:73], v[102:103] op_sel_hi:[1,0]
	v_pk_mul_f32 v[4:5], v[74:75], v[102:103] op_sel_hi:[1,0]
	v_pk_mul_f32 v[2:3], v[10:11], v[2:3] op_sel_hi:[0,1]
	v_pk_mul_f32 v[4:5], v[10:11], v[4:5] op_sel_hi:[0,1]
	ds_write2_b32 v56, v2, v3 offset1:1
	ds_write2_b32 v56, v4, v5 offset0:2 offset1:3
	s_nop 0
	s_waitcnt vmcnt(10)
	v_pk_mul_f32 v[2:3], v[76:77], v[104:105] op_sel_hi:[1,0]
	v_pk_mul_f32 v[4:5], v[78:79], v[104:105] op_sel_hi:[1,0]
	v_pk_mul_f32 v[2:3], v[10:11], v[2:3] op_sel_hi:[0,1]
	v_pk_mul_f32 v[4:5], v[10:11], v[4:5] op_sel_hi:[0,1]
	ds_write2_b32 v57, v2, v3 offset1:1
	ds_write2_b32 v57, v4, v5 offset0:2 offset1:3
	s_nop 0
	s_waitcnt vmcnt(8)
	v_pk_mul_f32 v[2:3], v[80:81], v[106:107] op_sel_hi:[1,0]
	v_pk_mul_f32 v[4:5], v[82:83], v[106:107] op_sel_hi:[1,0]
	v_pk_mul_f32 v[2:3], v[10:11], v[2:3] op_sel_hi:[0,1]
	v_pk_mul_f32 v[4:5], v[10:11], v[4:5] op_sel_hi:[0,1]
	ds_write2_b32 v58, v2, v3 offset1:1
	ds_write2_b32 v58, v4, v5 offset0:2 offset1:3
	s_nop 0
	s_waitcnt vmcnt(6)
	v_pk_mul_f32 v[2:3], v[84:85], v[108:109] op_sel_hi:[1,0]
	v_pk_mul_f32 v[4:5], v[86:87], v[108:109] op_sel_hi:[1,0]
	v_pk_mul_f32 v[2:3], v[10:11], v[2:3] op_sel_hi:[0,1]
	v_pk_mul_f32 v[4:5], v[10:11], v[4:5] op_sel_hi:[0,1]
	ds_write2_b32 v59, v2, v3 offset1:1
	ds_write2_b32 v59, v4, v5 offset0:2 offset1:3
	s_nop 0
	s_waitcnt vmcnt(4)
	v_pk_mul_f32 v[2:3], v[88:89], v[110:111] op_sel_hi:[1,0]
	v_pk_mul_f32 v[4:5], v[90:91], v[110:111] op_sel_hi:[1,0]
	v_pk_mul_f32 v[2:3], v[10:11], v[2:3] op_sel_hi:[0,1]
	v_pk_mul_f32 v[4:5], v[10:11], v[4:5] op_sel_hi:[0,1]
	ds_write2_b32 v60, v2, v3 offset1:1
	ds_write2_b32 v60, v4, v5 offset0:2 offset1:3
	s_nop 0
	s_waitcnt vmcnt(2)
	v_pk_mul_f32 v[2:3], v[92:93], v[112:113] op_sel_hi:[1,0]
	v_pk_mul_f32 v[4:5], v[94:95], v[112:113] op_sel_hi:[1,0]
	v_pk_mul_f32 v[2:3], v[10:11], v[2:3] op_sel_hi:[0,1]
	v_pk_mul_f32 v[4:5], v[10:11], v[4:5] op_sel_hi:[0,1]
	ds_write2_b32 v61, v2, v3 offset1:1
	ds_write2_b32 v61, v4, v5 offset0:2 offset1:3
	s_add_u32 s12, s1, s15
	s_addc_u32 s13, s3, 0
	s_add_i32 s25, s25, s24
	s_add_i32 s4, s4, s7
	s_cmpk_gt_i32 s25, 0x57f
	s_waitcnt vmcnt(0)
	v_pk_mul_f32 v[2:3], v[96:97], v[118:119] op_sel_hi:[1,0]
	v_pk_mul_f32 v[4:5], v[98:99], v[118:119] op_sel_hi:[1,0]
	v_pk_mul_f32 v[2:3], v[10:11], v[2:3] op_sel_hi:[0,1]
	v_pk_mul_f32 v[4:5], v[10:11], v[4:5] op_sel_hi:[0,1]
	ds_write2_b32 v62, v2, v3 offset1:1
	ds_write2_b32 v62, v4, v5 offset0:2 offset1:3
	s_waitcnt lgkmcnt(0)
	s_barrier
	ds_read2_b32 v[12:13], v51 offset0:129 offset1:193
	ds_read2st64_b32 v[10:11], v51 offset1:1
	v_add_u32_e32 v4, 12, v51
	ds_read2st64_b32 v[16:17], v4 offset0:6 offset1:7
	v_add_u32_e32 v5, 28, v51
	s_waitcnt lgkmcnt(2)
	v_rndne_f32_e32 v3, v12
	s_waitcnt lgkmcnt(1)
	v_rndne_f32_e32 v2, v10
	v_cvt_i32_f32_e32 v3, v3
	v_cvt_i32_f32_e32 v2, v2
	s_waitcnt lgkmcnt(0)
	v_rndne_f32_e32 v4, v16
	v_cvt_i32_f32_e32 v4, v4
	v_med3_i32 v3, v3, s71, v235
	v_med3_i32 v2, v2, s71, v235
	v_lshlrev_b32_e32 v3, 8, v3
	v_perm_b32 v2, v3, v2, s49
	v_add_u32_e32 v3, 8, v51
	ds_read2st64_b32 v[14:15], v3 offset0:4 offset1:5
	v_med3_i32 v4, v4, s71, v235
	v_lshlrev_b32_e32 v4, 24, v4
	ds_read2st64_b32 v[24:25], v5 offset0:14 offset1:15
	v_add_u32_e32 v10, 44, v51
	s_waitcnt lgkmcnt(1)
	v_rndne_f32_e32 v3, v14
	v_cvt_i32_f32_e32 v3, v3
	ds_read2st64_b32 v[32:33], v10 offset0:22 offset1:23
	s_waitcnt lgkmcnt(1)
	v_rndne_f32_e32 v5, v24
	v_cvt_i32_f32_e32 v5, v5
	v_med3_i32 v3, v3, s71, v235
	v_lshlrev_b32_e32 v3, 16, v3
	v_and_b32_e32 v3, 0xff0000, v3
	v_or3_b32 v2, v2, v3, v4
	v_add_u32_e32 v4, 20, v51
	v_add_u32_e32 v3, 16, v51
	ds_read2st64_b32 v[20:21], v4 offset0:10 offset1:11
	ds_read2st64_b32 v[18:19], v3 offset0:8 offset1:9
	v_med3_i32 v5, v5, s71, v235
	v_lshlrev_b32_e32 v5, 24, v5
	s_waitcnt lgkmcnt(2)
	v_rndne_f32_e32 v10, v32
	s_waitcnt lgkmcnt(1)
	v_rndne_f32_e32 v4, v20
	s_waitcnt lgkmcnt(0)
	v_rndne_f32_e32 v3, v18
	v_cvt_i32_f32_e32 v4, v4
	v_cvt_i32_f32_e32 v3, v3
	v_cvt_i32_f32_e32 v10, v10
	v_add_u32_e32 v12, 60, v51
	v_med3_i32 v4, v4, s71, v235
	v_med3_i32 v3, v3, s71, v235
	v_lshlrev_b32_e32 v4, 8, v4
	v_perm_b32 v3, v4, v3, s49
	v_add_u32_e32 v4, 24, v51
	ds_read2st64_b32 v[22:23], v4 offset0:12 offset1:13
	v_med3_i32 v10, v10, s71, v235
	v_lshlrev_b32_e32 v10, 24, v10
	ds_read2st64_b32 v[40:41], v12 offset0:30 offset1:31
	s_waitcnt lgkmcnt(1)
	v_rndne_f32_e32 v4, v22
	v_cvt_i32_f32_e32 v4, v4
	s_waitcnt lgkmcnt(0)
	v_rndne_f32_e32 v12, v40
	v_cvt_i32_f32_e32 v12, v12
	v_med3_i32 v4, v4, s71, v235
	v_lshlrev_b32_e32 v4, 16, v4
	v_and_b32_e32 v4, 0xff0000, v4
	v_or3_b32 v3, v3, v4, v5
	v_add_u32_e32 v5, 36, v51
	v_add_u32_e32 v4, 32, v51
	ds_read2st64_b32 v[28:29], v5 offset0:18 offset1:19
	ds_read2st64_b32 v[26:27], v4 offset0:16 offset1:17
	v_med3_i32 v12, v12, s71, v235
	v_lshlrev_b32_e32 v12, 24, v12
	s_waitcnt lgkmcnt(1)
	v_rndne_f32_e32 v5, v28
	s_waitcnt lgkmcnt(0)
	v_rndne_f32_e32 v4, v26
	v_cvt_i32_f32_e32 v5, v5
	v_cvt_i32_f32_e32 v4, v4
	v_med3_i32 v5, v5, s71, v235
	v_med3_i32 v4, v4, s71, v235
	v_lshlrev_b32_e32 v5, 8, v5
	v_perm_b32 v4, v5, v4, s49
	v_add_u32_e32 v5, 40, v51
	ds_read2st64_b32 v[30:31], v5 offset0:20 offset1:21
	s_waitcnt lgkmcnt(0)
	v_rndne_f32_e32 v5, v30
	v_cvt_i32_f32_e32 v5, v5
	v_med3_i32 v5, v5, s71, v235
	v_lshlrev_b32_e32 v5, 16, v5
	v_and_b32_e32 v5, 0xff0000, v5
	v_or3_b32 v4, v4, v5, v10
	v_add_u32_e32 v10, 52, v51
	v_add_u32_e32 v5, 48, v51
	ds_read2st64_b32 v[36:37], v10 offset0:26 offset1:27
	ds_read2st64_b32 v[34:35], v5 offset0:24 offset1:25
	s_waitcnt lgkmcnt(1)
	v_rndne_f32_e32 v10, v36
	s_waitcnt lgkmcnt(0)
	v_rndne_f32_e32 v5, v34
	v_cvt_i32_f32_e32 v10, v10
	v_cvt_i32_f32_e32 v5, v5
	v_med3_i32 v10, v10, s71, v235
	v_med3_i32 v5, v5, s71, v235
	v_lshlrev_b32_e32 v10, 8, v10
	v_perm_b32 v5, v10, v5, s49
	v_add_u32_e32 v10, 56, v51
	ds_read2st64_b32 v[38:39], v10 offset0:28 offset1:29
	s_waitcnt lgkmcnt(0)
	v_rndne_f32_e32 v10, v38
	v_cvt_i32_f32_e32 v10, v10
	v_med3_i32 v10, v10, s71, v235
	v_lshlrev_b32_e32 v10, 16, v10
	v_and_b32_e32 v10, 0xff0000, v10
	v_or3_b32 v5, v5, v10, v12
	v_or_b32_e32 v10, s14, v53
	v_add_u32_e32 v64, v10, v52
	v_ashrrev_i32_e32 v65, 31, v64
	v_lshlrev_b64 v[64:65], 11, v[64:65]
	v_lshl_add_u64 v[64:65], s[12:13], 0, v[64:65]
	v_lshl_add_u64 v[64:65], v[64:65], 0, v[114:115]
	global_store_dwordx4 v[64:65], v[2:5], off
	v_rndne_f32_e32 v12, v41
	v_cvt_i32_f32_e32 v12, v12
	v_rndne_f32_e32 v3, v13
	v_rndne_f32_e32 v2, v11
	v_cvt_i32_f32_e32 v3, v3
	v_cvt_i32_f32_e32 v2, v2
	v_rndne_f32_e32 v4, v17
	v_cvt_i32_f32_e32 v4, v4
	v_med3_i32 v3, v3, s71, v235
	v_med3_i32 v2, v2, s71, v235
	v_lshlrev_b32_e32 v3, 8, v3
	v_perm_b32 v2, v3, v2, s49
	v_rndne_f32_e32 v3, v15
	v_cvt_i32_f32_e32 v3, v3
	v_med3_i32 v4, v4, s71, v235
	v_lshlrev_b32_e32 v4, 24, v4
	v_rndne_f32_e32 v5, v25
	v_med3_i32 v3, v3, s71, v235
	v_lshlrev_b32_e32 v3, 16, v3
	v_and_b32_e32 v3, 0xff0000, v3
	v_or3_b32 v2, v2, v3, v4
	v_rndne_f32_e32 v4, v21
	v_rndne_f32_e32 v3, v19
	v_cvt_i32_f32_e32 v4, v4
	v_cvt_i32_f32_e32 v3, v3
	v_cvt_i32_f32_e32 v5, v5
	v_rndne_f32_e32 v11, v33
	v_med3_i32 v4, v4, s71, v235
	v_med3_i32 v3, v3, s71, v235
	v_lshlrev_b32_e32 v4, 8, v4
	v_perm_b32 v3, v4, v3, s49
	v_rndne_f32_e32 v4, v23
	v_cvt_i32_f32_e32 v4, v4
	v_med3_i32 v5, v5, s71, v235
	v_lshlrev_b32_e32 v5, 24, v5
	v_cvt_i32_f32_e32 v11, v11
	v_med3_i32 v4, v4, s71, v235
	v_lshlrev_b32_e32 v4, 16, v4
	v_and_b32_e32 v4, 0xff0000, v4
	v_or3_b32 v3, v3, v4, v5
	v_rndne_f32_e32 v5, v29
	v_rndne_f32_e32 v4, v27
	v_cvt_i32_f32_e32 v5, v5
	v_cvt_i32_f32_e32 v4, v4
	v_med3_i32 v11, v11, s71, v235
	v_lshlrev_b32_e32 v11, 24, v11
	v_med3_i32 v5, v5, s71, v235
	v_med3_i32 v4, v4, s71, v235
	v_lshlrev_b32_e32 v5, 8, v5
	v_perm_b32 v4, v5, v4, s49
	v_rndne_f32_e32 v5, v31
	v_cvt_i32_f32_e32 v5, v5
	v_med3_i32 v12, v12, s71, v235
	v_lshlrev_b32_e32 v12, 24, v12
	v_add_u32_e32 v10, v10, v54
	v_med3_i32 v5, v5, s71, v235
	v_lshlrev_b32_e32 v5, 16, v5
	v_and_b32_e32 v5, 0xff0000, v5
	v_or3_b32 v4, v4, v5, v11
	v_rndne_f32_e32 v11, v37
	v_rndne_f32_e32 v5, v35
	v_cvt_i32_f32_e32 v11, v11
	v_cvt_i32_f32_e32 v5, v5
	v_med3_i32 v11, v11, s71, v235
	v_med3_i32 v5, v5, s71, v235
	v_lshlrev_b32_e32 v11, 8, v11
	v_perm_b32 v5, v11, v5, s49
	v_rndne_f32_e32 v11, v39
	v_cvt_i32_f32_e32 v11, v11
	v_med3_i32 v11, v11, s71, v235
	v_lshlrev_b32_e32 v11, 16, v11
	v_and_b32_e32 v11, 0xff0000, v11
	v_or3_b32 v5, v5, v11, v12
	v_ashrrev_i32_e32 v11, 31, v10
	v_lshlrev_b64 v[10:11], 11, v[10:11]
	v_lshl_add_u64 v[10:11], s[12:13], 0, v[10:11]
	v_lshl_add_u64 v[10:11], v[10:11], 0, v[114:115]
	global_store_dwordx4 v[10:11], v[2:5], off
	s_barrier
	s_cbranch_scc0 .LBB0_1034
